# L2/TLB prefetch of the residual rows (xb tile block) 10 K-iterations before the FFN1-down epilogue
# baseline (speedup 1.0000x reference)
.LBB0_234:
	s_or_b64 exec, exec, s[4:5]
	s_waitcnt lgkmcnt(0)
	s_barrier
	v_lshrrev_b32_e32 v249, 1, v240
	v_lshlrev_b32_e32 v249, 11, v249
	v_and_b32_e32 v248, 1, v240
	v_lshl_or_b32 v249, v248, 8, v249
	s_load_dwordx2 s[4:5], s[0:1], 0xa8
	v_mov_b32_e32 v8, v240
	s_waitcnt lgkmcnt(0)
	v_mov_b32_e32 v0, s5
	v_mov_b32_e32 v1, s4
	s_nop 0
	v_readfirstlane_b32 s7, v0
	v_mov_b32_e32 v0, s2
	v_readfirstlane_b32 s6, v1
	v_readfirstlane_b32 s33, v0
	v_mov_b32_e32 v0, s24
	s_cmpk_lt_i32 s33, 0x300
	s_cselect_b64 s[4:5], -1, 0
	v_readfirstlane_b32 s34, v0
	s_cmpk_gt_i32 s33, 0x2ff
	v_readfirstlane_b32 s35, v8
	s_cbranch_scc1 .LBB0_236
	s_ashr_i32 s8, s33, 31
	s_lshr_b32 s8, s8, 29
	s_add_i32 s8, s33, s8
	s_ashr_i32 s9, s8, 3
	s_and_b32 s8, s8, -8
	s_sub_i32 s8, s33, s8
	s_cmp_lt_i32 s8, 0
	s_movk_i32 s10, 0x61
	s_cselect_b32 s10, s10, 0x60
	s_mul_i32 s8, s8, s10
	s_add_i32 s8, s8, s9
	s_ashr_i32 s9, s8, 31
	s_lshr_b32 s9, s9, 27
	s_add_i32 s9, s8, s9
	s_ashr_i32 s10, s9, 5
	s_and_b32 s9, s9, 0xffe0
	s_sub_i32 s8, s8, s9
	s_bfe_i32 s9, s8, 0x80000
	s_bfe_u32 s9, s9, 0x3000c
	s_add_i32 s9, s8, s9
	s_bfe_i32 s11, s9, 0x80000
	s_and_b32 s9, s9, 0xf8
	s_sub_i32 s8, s8, s9
	s_lshl_b32 s10, s10, 3
	s_sext_i32_i16 s11, s11
	s_sext_i32_i8 s8, s8
	s_add_i32 s56, s10, s8
	s_ashr_i32 s12, s11, 3

.LBB0_247:
	s_lshl_b32 s88, s56, 19
	s_lshl_b32 s89, s12, 9
	s_add_u32 s88, s88, s89
	s_add_u32 s88, s14, s88
	s_addc_u32 s89, s15, 0
	s_add_u32 s57, s26, 0x100
	s_addc_u32 s58, s27, 0
	s_mov_b32 s59, -2
	s_waitcnt lgkmcnt(0)
	s_setprio 0
	s_cmpk_lt_u32 s35, 0x100
	s_cbranch_scc1 .Lg248_noy
	s_setprio 1
	s_barrier

.LBB0_248:
	ds_read_b128 v[144:147], v151
	ds_read_b128 v[156:159], v151 offset:1024
	ds_read_b128 v[160:163], v151 offset:2048
	ds_read_b128 v[164:167], v151 offset:3072
	s_add_u32 s26, s20, 0x100
	s_addc_u32 s27, s21, 0
	s_cmp_eq_u32 s59, 40
	s_cselect_b32 s31, s9, s27
	s_cselect_b32 s30, s8, s26
	s_cselect_b32 s29, s11, s58
	s_cselect_b32 s28, s10, s57
	s_cmp_eq_u32 s59, 20
	s_cbranch_scc0 .Lpf_dn1_skip
	global_load_dword v248, v249, s[88:89]
	global_load_dword v248, v249, s[88:89] offset:128
.Lpf_dn1_skip:
	s_add_i32 m0, s41, 0xc000
	ds_read_b128 v[168:171], v152
	ds_read_b128 v[172:175], v152 offset:1024
	ds_read_b128 v[176:179], v152 offset:2048
	ds_read_b128 v[180:183], v152 offset:3072
	ds_read_b128 v[184:187], v152 offset:4096
	ds_read_b128 v[188:191], v152 offset:5120
	ds_read_b128 v[192:195], v152 offset:6144
	ds_read_b128 v[196:199], v152 offset:7168
	global_load_lds_dwordx4 v136, s[20:21]
	s_add_i32 m0, s41, 0xe000
	s_nop 0
	global_load_lds_dwordx4 v138, s[20:21]
	s_waitcnt lgkmcnt(8)
	s_barrier
	s_waitcnt lgkmcnt(0)
	s_waitcnt lgkmcnt(0)
	v_mfma_f32_16x16x32_bf16 v[124:127], v[144:147], v[168:171], v[124:127]
	v_mfma_f32_16x16x32_bf16 v[120:123], v[160:163], v[168:171], v[120:123]
	v_mfma_f32_16x16x32_bf16 v[108:111], v[144:147], v[176:179], v[108:111]
	v_mfma_f32_16x16x32_bf16 v[104:107], v[160:163], v[176:179], v[104:107]
	v_mfma_f32_16x16x32_bf16 v[92:95], v[144:147], v[184:187], v[92:95]
	v_mfma_f32_16x16x32_bf16 v[88:91], v[160:163], v[184:187], v[88:91]
	v_mfma_f32_16x16x32_bf16 v[76:79], v[144:147], v[192:195], v[76:79]
	v_mfma_f32_16x16x32_bf16 v[72:75], v[160:163], v[192:195], v[72:75]
	v_mfma_f32_16x16x32_bf16 v[124:127], v[156:159], v[172:175], v[124:127]
	v_mfma_f32_16x16x32_bf16 v[120:123], v[164:167], v[172:175], v[120:123]
	v_mfma_f32_16x16x32_bf16 v[108:111], v[156:159], v[180:183], v[108:111]
	v_mfma_f32_16x16x32_bf16 v[104:107], v[164:167], v[180:183], v[104:107]
	v_mfma_f32_16x16x32_bf16 v[92:95], v[156:159], v[188:191], v[92:95]
	v_mfma_f32_16x16x32_bf16 v[88:91], v[164:167], v[188:191], v[88:91]
	v_mfma_f32_16x16x32_bf16 v[76:79], v[156:159], v[196:199], v[76:79]
	v_mfma_f32_16x16x32_bf16 v[72:75], v[164:167], v[196:199], v[72:75]
	s_barrier
	s_add_i32 s20, s51, s40
	s_add_u32 s80, s28, 0x80
	s_addc_u32 s81, s29, 0
	s_mov_b32 m0, s20
	ds_read_b128 v[200:203], v153
	ds_read_b128 v[204:207], v153 offset:1024
	ds_read_b128 v[208:211], v153 offset:2048
	ds_read_b128 v[212:215], v153 offset:3072
	global_load_lds_dwordx4 v130, s[28:29]
	s_add_i32 m0, s20, 0x2000
	s_nop 0
	global_load_lds_dwordx4 v134, s[28:29]
	s_waitcnt vmcnt(10)
	s_barrier
	s_waitcnt lgkmcnt(0)
	s_waitcnt lgkmcnt(0)
	v_mfma_f32_16x16x32_bf16 v[116:119], v[200:203], v[168:171], v[116:119]
	v_mfma_f32_16x16x32_bf16 v[112:115], v[208:211], v[168:171], v[112:115]
	v_mfma_f32_16x16x32_bf16 v[100:103], v[200:203], v[176:179], v[100:103]
	v_mfma_f32_16x16x32_bf16 v[96:99], v[208:211], v[176:179], v[96:99]
	v_mfma_f32_16x16x32_bf16 v[84:87], v[200:203], v[184:187], v[84:87]
	v_mfma_f32_16x16x32_bf16 v[80:83], v[208:211], v[184:187], v[80:83]
	v_mfma_f32_16x16x32_bf16 v[68:71], v[200:203], v[192:195], v[68:71]
	v_mfma_f32_16x16x32_bf16 v[64:67], v[208:211], v[192:195], v[64:67]
	v_mfma_f32_16x16x32_bf16 v[116:119], v[204:207], v[172:175], v[116:119]
	v_mfma_f32_16x16x32_bf16 v[112:115], v[212:215], v[172:175], v[112:115]
	v_mfma_f32_16x16x32_bf16 v[100:103], v[204:207], v[180:183], v[100:103]
	v_mfma_f32_16x16x32_bf16 v[96:99], v[212:215], v[180:183], v[96:99]
	v_mfma_f32_16x16x32_bf16 v[84:87], v[204:207], v[188:191], v[84:87]
	v_mfma_f32_16x16x32_bf16 v[80:83], v[212:215], v[188:191], v[80:83]
	v_mfma_f32_16x16x32_bf16 v[68:71], v[204:207], v[196:199], v[68:71]
	v_mfma_f32_16x16x32_bf16 v[64:67], v[212:215], v[196:199], v[64:67]
	s_mov_b32 m0, s41
	s_add_u32 s82, s30, 0x80
	s_addc_u32 s83, s31, 0
	s_barrier
	ds_read_b128 v[168:171], v152 offset:16384
	ds_read_b128 v[172:175], v152 offset:17408
	ds_read_b128 v[176:179], v152 offset:18432
	ds_read_b128 v[180:183], v152 offset:19456
	ds_read_b128 v[184:187], v152 offset:20480
	ds_read_b128 v[188:191], v152 offset:21504
	ds_read_b128 v[192:195], v152 offset:22528
	ds_read_b128 v[196:199], v152 offset:23552
	global_load_lds_dwordx4 v128, s[30:31]
	s_mov_b32 m0, s42
	s_nop 0
	global_load_lds_dwordx4 v132, s[30:31]
	s_barrier
	s_waitcnt lgkmcnt(0)
	s_waitcnt lgkmcnt(0)
	v_mfma_f32_16x16x32_bf16 v[60:63], v[144:147], v[168:171], v[60:63]
	v_mfma_f32_16x16x32_bf16 v[56:59], v[160:163], v[168:171], v[56:59]
	v_mfma_f32_16x16x32_bf16 v[44:47], v[144:147], v[176:179], v[44:47]
	v_mfma_f32_16x16x32_bf16 v[40:43], v[160:163], v[176:179], v[40:43]
	v_mfma_f32_16x16x32_bf16 v[28:31], v[144:147], v[184:187], v[28:31]
	v_mfma_f32_16x16x32_bf16 v[24:27], v[160:163], v[184:187], v[24:27]
	v_mfma_f32_16x16x32_bf16 v[12:15], v[144:147], v[192:195], v[12:15]
	v_mfma_f32_16x16x32_bf16 v[8:11], v[160:163], v[192:195], v[8:11]
	v_mfma_f32_16x16x32_bf16 v[60:63], v[156:159], v[172:175], v[60:63]
	v_mfma_f32_16x16x32_bf16 v[56:59], v[164:167], v[172:175], v[56:59]
	v_mfma_f32_16x16x32_bf16 v[44:47], v[156:159], v[180:183], v[44:47]
	v_mfma_f32_16x16x32_bf16 v[40:43], v[164:167], v[180:183], v[40:43]
	v_mfma_f32_16x16x32_bf16 v[28:31], v[156:159], v[188:191], v[28:31]
	v_mfma_f32_16x16x32_bf16 v[24:27], v[164:167], v[188:191], v[24:27]
	v_mfma_f32_16x16x32_bf16 v[12:15], v[156:159], v[196:199], v[12:15]
	v_mfma_f32_16x16x32_bf16 v[8:11], v[164:167], v[196:199], v[8:11]
	s_barrier
	s_add_u32 s20, s28, 0xb0000
	s_addc_u32 s21, s29, 0
	s_add_i32 s60, s52, s40
	s_mov_b32 m0, s60
	s_nop 0
	global_load_lds_dwordx4 v130, s[20:21]
	s_add_i32 m0, s60, 0x2000
	s_nop 0
	global_load_lds_dwordx4 v134, s[20:21]
	s_waitcnt vmcnt(8)
	s_barrier
	v_mfma_f32_16x16x32_bf16 v[52:55], v[200:203], v[168:171], v[52:55]
	v_mfma_f32_16x16x32_bf16 v[48:51], v[208:211], v[168:171], v[48:51]
	v_mfma_f32_16x16x32_bf16 v[36:39], v[200:203], v[176:179], v[36:39]
	v_mfma_f32_16x16x32_bf16 v[32:35], v[208:211], v[176:179], v[32:35]
	v_mfma_f32_16x16x32_bf16 v[20:23], v[200:203], v[184:187], v[20:23]
	v_mfma_f32_16x16x32_bf16 v[16:19], v[208:211], v[184:187], v[16:19]
	v_mfma_f32_16x16x32_bf16 v[4:7], v[200:203], v[192:195], v[4:7]
	v_mfma_f32_16x16x32_bf16 v[0:3], v[208:211], v[192:195], v[0:3]
	v_mfma_f32_16x16x32_bf16 v[52:55], v[204:207], v[172:175], v[52:55]
	v_mfma_f32_16x16x32_bf16 v[48:51], v[212:215], v[172:175], v[48:51]
	v_mfma_f32_16x16x32_bf16 v[36:39], v[204:207], v[180:183], v[36:39]
	v_mfma_f32_16x16x32_bf16 v[32:35], v[212:215], v[180:183], v[32:35]
	v_mfma_f32_16x16x32_bf16 v[20:23], v[204:207], v[188:191], v[20:23]
	v_mfma_f32_16x16x32_bf16 v[16:19], v[212:215], v[188:191], v[16:19]
	v_mfma_f32_16x16x32_bf16 v[4:7], v[204:207], v[196:199], v[4:7]
	v_mfma_f32_16x16x32_bf16 v[0:3], v[212:215], v[196:199], v[0:3]
	s_add_i32 s60, 0, 0x18000
	v_add_u32_e32 v155, s60, v149
	s_barrier

	.amdhsa_kernel _Z9hymba_fwd6Params
		.amdhsa_group_segment_fixed_size 0
		.amdhsa_private_segment_fixed_size 0
		.amdhsa_kernarg_size 432
		.amdhsa_user_sgpr_count 2
		.amdhsa_user_sgpr_dispatch_ptr 0
		.amdhsa_user_sgpr_queue_ptr 0
		.amdhsa_user_sgpr_kernarg_segment_ptr 1
		.amdhsa_user_sgpr_dispatch_id 0
		.amdhsa_user_sgpr_kernarg_preload_length 0
		.amdhsa_user_sgpr_kernarg_preload_offset 0
		.amdhsa_user_sgpr_private_segment_size 0
		.amdhsa_uses_dynamic_stack 0
		.amdhsa_enable_private_segment 0
		.amdhsa_system_sgpr_workgroup_id_x 1
		.amdhsa_system_sgpr_workgroup_id_y 0
		.amdhsa_system_sgpr_workgroup_id_z 0
		.amdhsa_system_sgpr_workgroup_info 0
		.amdhsa_system_vgpr_workitem_id 2
		.amdhsa_next_free_vgpr 250
		.amdhsa_next_free_sgpr 97
		.amdhsa_accum_offset 252
		.amdhsa_reserve_vcc 1
		.amdhsa_float_round_mode_32 0
		.amdhsa_float_round_mode_16_64 0
		.amdhsa_float_denorm_mode_32 3
		.amdhsa_float_denorm_mode_16_64 3
		.amdhsa_dx10_clamp 1
		.amdhsa_ieee_mode 1
		.amdhsa_fp16_overflow 0
		.amdhsa_tg_split 0
		.amdhsa_exception_fp_ieee_invalid_op 0
		.amdhsa_exception_fp_denorm_src 0
		.amdhsa_exception_fp_ieee_div_zero 0
		.amdhsa_exception_fp_ieee_overflow 0
		.amdhsa_exception_fp_ieee_underflow 0
		.amdhsa_exception_fp_ieee_inexact 0
		.amdhsa_exception_int_div_zero 0
	.end_amdhsa_kernel

amdhsa.kernels:
  - .agpr_count:     0
    .args:
      - .offset:         0
        .size:           176
        .value_kind:     by_value
      - .offset:         176
        .size:           4
        .value_kind:     hidden_block_count_x
      - .offset:         180
        .size:           4
        .value_kind:     hidden_block_count_y
      - .offset:         184
        .size:           4
        .value_kind:     hidden_block_count_z
      - .offset:         188
        .size:           2
        .value_kind:     hidden_group_size_x
      - .offset:         190
        .size:           2
        .value_kind:     hidden_group_size_y
      - .offset:         192
        .size:           2
        .value_kind:     hidden_group_size_z
      - .offset:         194
        .size:           2
        .value_kind:     hidden_remainder_x
      - .offset:         196
        .size:           2
        .value_kind:     hidden_remainder_y
      - .offset:         198
        .size:           2
        .value_kind:     hidden_remainder_z
      - .offset:         216
        .size:           8
        .value_kind:     hidden_global_offset_x
      - .offset:         224
        .size:           8
        .value_kind:     hidden_global_offset_y
      - .offset:         232
        .size:           8
        .value_kind:     hidden_global_offset_z
      - .offset:         240
        .size:           2
        .value_kind:     hidden_grid_dims
      - .offset:         264
        .size:           8
        .value_kind:     hidden_multigrid_sync_arg
      - .offset:         296
        .size:           4
        .value_kind:     hidden_dynamic_lds_size
    .group_segment_fixed_size: 0
    .kernarg_segment_align: 8
    .kernarg_segment_size: 432
    .language:       OpenCL C
    .language_version:
      - 2
      - 0
    .max_flat_workgroup_size: 512
    .name:           _Z9hymba_fwd6Params
    .private_segment_fixed_size: 0
    .sgpr_count:     103
    .sgpr_spill_count: 0
    .symbol:         _Z9hymba_fwd6Params.kd
    .uniform_work_group_size: 1
    .uses_dynamic_stack: false
    .vgpr_count:     250
    .vgpr_spill_count: 0
    .wavefront_size: 64
